# attention-second-tile-prefetch
# baseline (speedup 1.0000x reference)
; #define LAS __attribute__((address_space(3)))
; #define X make_ctx(lds_raw)
;     ...
;         __syncthreads();
;         { const int i = X.tid >> 2, c = X.tid & 3; const int t = tb + (128 * n + i) * r; const bf16_t* src = proj + (size_t)t * NMAIN + C_AQ + h * 64 + 16 * c;
;           *(LAS u32x4*)(Qs + i * QP + 16 * c) = *(const u32x4*)src; *(LAS u32x4*)(Qs + i * QP + 16 * c + 8) = *(const u32x4*)(src + 8); }
;         for (int blk = reuse ? 1 : 0; blk < 2; ++blk) {
;             const int half = blk ? cur_half : prev_half;
;             { const int j = X.tid >> 2, c = X.tid & 3; int m = 128 * (n - 1 + blk) + j; m = m < 0 ? 0 : m; const int t = tb + m * r;
;               const bf16_t* src = proj + (size_t)t * NMAIN + C_AK + h * 64 + 16 * c;
;               *(LAS u32x4*)(Ks + (half * 128 + j) * QP + 16 * c) = *(const u32x4*)src; *(LAS u32x4*)(Ks + (half * 128 + j) * QP + 16 * c + 8) = *(const u32x4*)(src + 8); }
; #pragma unroll
;             for (int q = 0; q < 2; ++q) { const int idx = X.tid + 512 * q, j = idx & 127, c = idx >> 7; int m = 128 * (n - 1 + blk) + j; m = m < 0 ? 0 : m; const int t = tb + m * r;
;                 const u32x4 wv = *(const u32x4*)(proj + (size_t)t * NMAIN + C_AV + h * 64 + 8 * c);
;                 LAS bf16_t* vp = Vt + (8 * c) * VP + half * 128 + j;
;                 vp[0 * VP] = (bf16_t)(wv.x & 0xffff); vp[1 * VP] = (bf16_t)(wv.x >> 16); vp[2 * VP] = (bf16_t)(wv.y & 0xffff); vp[3 * VP] = (bf16_t)(wv.y >> 16);
;                 vp[4 * VP] = (bf16_t)(wv.z & 0xffff); vp[5 * VP] = (bf16_t)(wv.z >> 16); vp[6 * VP] = (bf16_t)(wv.w & 0xffff); vp[7 * VP] = (bf16_t)(wv.w >> 16); }
.Lapf_steady:
	s_waitcnt vmcnt(5)
	v_cmp_ne_u32_e32 vcc, 1, v1
	v_lshl_add_u32 v1, s27, 7, v39
	v_lshl_add_u32 v17, s27, 8, v40
	v_mad_u64_u32 v[76:77], s[42:43], v1, s34, v[8:9]
	v_add_u32_e32 v1, v17, v41
	v_add_u32_e32 v17, v17, v42
	s_and_b64 vcc, exec, vcc
	ds_write_b128 v10, v[110:113]
	ds_write_b128 v10, v[114:117] offset:16
	ds_write_b128 v76, v[118:121] offset:18432
	ds_write_b128 v76, v[122:125] offset:18448
	ds_write_b16 v1, v126 offset:55296
	ds_write_b16_d16_hi v1, v126 offset:55824
	ds_write_b16 v1, v127 offset:56352
	ds_write_b16_d16_hi v1, v127 offset:56880
	ds_write_b16 v1, v128 offset:57408
	ds_write_b16_d16_hi v1, v128 offset:57936
	ds_write_b16 v1, v129 offset:58464
	ds_write_b16_d16_hi v1, v129 offset:58992
	ds_write_b16 v17, v130 offset:55296
	ds_write_b16_d16_hi v17, v130 offset:55824
	ds_write_b16 v17, v131 offset:56352
	ds_write_b16_d16_hi v17, v131 offset:56880
	ds_write_b16 v17, v132 offset:57408
	ds_write_b16_d16_hi v17, v132 offset:57936
	ds_write_b16 v17, v133 offset:58464
	ds_write_b16_d16_hi v17, v133 offset:58992
	s_cbranch_vccz .LBB0_334
	s_cmp_eq_u32 s41, s30
	s_cbranch_scc1 .Lapf_b333_orig
	v_lshl_add_u32 v0, s40, 7, v39
	v_lshl_add_u32 v2, s40, 8, v40
	v_mad_u64_u32 v[0:1], s[24:25], v0, s34, v[8:9]
	v_add_u32_e32 v1, v2, v41
	v_add_u32_e32 v2, v2, v42
	ds_write_b128 v0, v[152:155] offset:18432
	ds_write_b128 v0, v[156:159] offset:18448
	ds_write_b16 v1, v160 offset:55296
	ds_write_b16_d16_hi v1, v160 offset:55824
	ds_write_b16 v1, v161 offset:56352
	ds_write_b16_d16_hi v1, v161 offset:56880
	ds_write_b16 v1, v162 offset:57408
	ds_write_b16_d16_hi v1, v162 offset:57936
	ds_write_b16 v1, v163 offset:58464
	ds_write_b16_d16_hi v1, v163 offset:58992
	ds_write_b16 v2, v164 offset:55296
	ds_write_b16_d16_hi v2, v164 offset:55824
	ds_write_b16 v2, v165 offset:56352
	ds_write_b16_d16_hi v2, v165 offset:56880
	ds_write_b16 v2, v166 offset:57408
	ds_write_b16_d16_hi v2, v166 offset:57936
	ds_write_b16 v2, v167 offset:58464
	ds_write_b16_d16_hi v2, v167 offset:58992
	s_branch .LBB0_334
.Lapf_b333_orig:
	v_max_i32_e32 v0, 0, v0
	v_lshlrev_b32_e32 v0, s97, v0
	v_add_u32_e32 v17, s44, v0
	v_mov_b64_e32 v[0:1], s[48:49]
	v_mad_i64_i32 v[52:53], s[26:27], v17, s35, v[0:1]
	v_lshl_add_u64 v[52:53], v[52:53], 0, s[24:25]
	v_lshl_add_u64 v[52:53], v[52:53], 0, v[2:3]
	v_or_b32_e32 v2, s45, v11
	v_lshlrev_b32_e32 v2, s97, v2
	s_mov_b64 s[26:27], 0x1e00
	v_add_u32_e32 v2, s44, v2
	v_lshl_add_u64 v[56:57], v[52:53], 0, s[26:27]
	v_add_co_u32_e32 v52, vcc, 0x1000, v52
	v_mad_i64_i32 v[0:1], s[26:27], v2, s35, v[0:1]
	s_nop 0
	v_addc_co_u32_e32 v53, vcc, 0, v53, vcc
	v_lshl_add_u64 v[0:1], v[0:1], 0, s[24:25]
	s_mov_b64 s[24:25], 0x2400
	global_load_dwordx4 v[52:55], v[52:53], off offset:3584
	s_nop 0
	global_load_dwordx4 v[56:59], v[56:57], off offset:16
	v_lshl_add_u64 v[0:1], v[0:1], 0, s[24:25]
	v_lshl_add_u64 v[60:61], v[12:13], 1, v[0:1]
	global_load_dwordx4 v[60:63], v[60:61], off
	v_lshl_add_u64 v[0:1], v[14:15], 1, v[0:1]
	global_load_dwordx4 v[64:67], v[0:1], off
	v_lshl_add_u32 v0, s40, 7, v39
	v_lshl_add_u32 v2, s40, 8, v40
	v_mad_u64_u32 v[0:1], s[24:25], v0, s34, v[8:9]
	v_add_u32_e32 v1, v2, v41
	v_add_u32_e32 v2, v2, v42
	s_waitcnt vmcnt(3)
	ds_write_b128 v0, v[52:55] offset:18432
	s_waitcnt vmcnt(2)
	ds_write_b128 v0, v[56:59] offset:18448
	s_waitcnt vmcnt(1)
	ds_write_b16 v1, v60 offset:55296
	ds_write_b16_d16_hi v1, v60 offset:55824
	ds_write_b16 v1, v61 offset:56352
	ds_write_b16_d16_hi v1, v61 offset:56880
	ds_write_b16 v1, v62 offset:57408
	ds_write_b16_d16_hi v1, v62 offset:57936
	ds_write_b16 v1, v63 offset:58464
	ds_write_b16_d16_hi v1, v63 offset:58992
	s_waitcnt vmcnt(0)
	ds_write_b16 v2, v64 offset:55296
	ds_write_b16_d16_hi v2, v64 offset:55824
	ds_write_b16 v2, v65 offset:56352
	ds_write_b16_d16_hi v2, v65 offset:56880
	ds_write_b16 v2, v66 offset:57408
	ds_write_b16_d16_hi v2, v66 offset:57936
	ds_write_b16 v2, v67 offset:58464
	ds_write_b16_d16_hi v2, v67 offset:58992
.LBB0_334:
	s_and_b64 s[24:25], s[50:51], exec
	s_cselect_b32 s43, s46, s40
	v_lshl_or_b32 v0, s43, 7, v43
	v_mad_u64_u32 v[0:1], s[24:25], v0, s34, v[4:5]
	s_waitcnt lgkmcnt(0)
	s_barrier
	ds_read_b128 v[52:55], v0 offset:18432
	ds_read_b128 v[56:59], v0 offset:18496
	ds_read_b128 v[60:63], v51
	ds_read_b128 v[64:67], v51 offset:64
	v_readlane_b32 s24, v254, 41
	s_add_i32 s98, s41, 1
	s_cmp_lt_i32 s98, s24
	s_cbranch_scc0 .Lapf_skip
	s_mul_hi_i32 s24, s98, 0x2aaaaaab
	s_lshr_b32 s25, s24, 31
	s_ashr_i32 s24, s24, 6
	s_add_i32 s24, s24, s25
	s_mul_i32 s25, s24, 0xfffffe80
	s_add_i32 s98, s98, s25
	s_and_b32 s25, s98, 31
	s_ashr_i32 s26, s98, 7
	s_cmp_eq_u32 s26, 1
	s_cselect_b32 s26, 2, 4
	s_cmpk_gt_u32 s98, 0x7f
	s_cselect_b32 s99, s26, 0
	s_lshr_b32 s26, 32, s99
	s_sub_i32 s27, 5, s99
	s_lshr_b32 s27, s25, s27
	s_add_i32 s26, s26, -1
	s_lshl_b32 s24, s24, 12
	s_and_b32 s26, s26, s25
	s_or_b32 s100, s27, s24
	s_lshl_b32 s24, s98, 1
	s_andn2_b32 s24, s24, 63
	s_lshl_b32 s101, s24, 1
	s_lshl_b32 s24, s26, 7
	s_cmp_gt_u32 s26, 0
	s_cselect_b32 s25, s26, -1
	s_lshl_b32 s27, s25, 7
	s_cmp_gt_i32 s25, -1
	s_cselect_b64 vcc, -1, 0
	v_add_u32_e32 v134, s24, v39
	v_add_u32_e32 v135, s27, v39
	v_or_b32_e32 v144, s27, v11
	v_max_i32_e32 v135, 0, v135
	v_cndmask_b32_e32 v144, 0, v144, vcc
	v_lshlrev_b32_e32 v134, s99, v134
	v_lshlrev_b32_e32 v135, s99, v135
	v_lshlrev_b32_e32 v144, s99, v144
	v_add_u32_e32 v134, s100, v134
	v_add_u32_e32 v135, s100, v135
	v_add_u32_e32 v144, s100, v144
	v_mov_b64_e32 v[136:137], s[48:49]
	v_mad_i64_i32 v[138:139], s[24:25], v134, s35, v[136:137]
	v_mad_i64_i32 v[146:147], s[24:25], v135, s35, v[136:137]
	v_mad_i64_i32 v[150:151], s[24:25], v144, s35, v[136:137]
	v_lshl_add_u32 v140, v6, 1, s101
	v_mov_b32_e32 v141, 0
	v_mov_b32_e32 v135, 0
	v_add_u32_e32 v134, 0x1800, v140
	v_add_u32_e32 v140, 0x1e00, v140
	v_lshl_add_u64 v[138:139], v[138:139], 0, v[134:135]
	v_lshl_add_u64 v[146:147], v[146:147], 0, v[140:141]
	v_lshl_add_u32 v134, v12, 1, s101
	v_lshl_add_u32 v140, v14, 1, s101
	v_add_u32_e32 v134, 0x2400, v134
	v_add_u32_e32 v140, 0x2400, v140
	v_lshl_add_u64 v[148:149], v[150:151], 0, v[134:135]
	v_lshl_add_u64 v[150:151], v[150:151], 0, v[140:141]
	s_cmp_lg_u32 s26, 0
	s_cbranch_scc1 .Lapf_noextra
	v_lshlrev_b32_e32 v168, s99, v11
	v_add_u32_e32 v168, s100, v168
	v_mad_i64_i32 v[170:171], s[24:25], v168, s35, v[136:137]
	v_lshl_add_u64 v[172:173], v[170:171], 0, v[134:135]
	v_lshl_add_u64 v[174:175], v[170:171], 0, v[140:141]
	global_load_dwordx4 v[152:155], v[138:139], off offset:1536
	global_load_dwordx4 v[156:159], v[138:139], off offset:1552
	global_load_dwordx4 v[160:163], v[172:173], off
	global_load_dwordx4 v[164:167], v[174:175], off
.Lapf_noextra:
	global_load_dwordx4 v[110:113], v[138:139], off
	global_load_dwordx4 v[114:117], v[138:139], off offset:16
	global_load_dwordx4 v[118:121], v[146:147], off
	global_load_dwordx4 v[122:125], v[146:147], off offset:16
	global_load_dwordx4 v[126:129], v[148:149], off
	global_load_dwordx4 v[130:133], v[150:151], off
